# v43 + in-proj epilogue: group-0 alignment barrier moved after the epilogue loads are issued (loads overlap the wait for the other wave group)
# baseline (speedup 1.0000x reference)
; #define PG8_STAGE(bufoff, gbase, voff) do { _Pragma("unroll") for (int _i = 0; _i < 2; ++_i) \
;         __builtin_amdgcn_global_load_lds((const unsigned*)((const char*)(gbase) + (voff)[_i]), (LAS unsigned*)(lds + (bufoff) + ldsw + _i * 8192), 16, 0, 0); } while (0)
; #define PG8_LDA(dst, b, h) do { _Pragma("unroll") for (int m = 0; m < 4; ++m) _Pragma("unroll") for (int k = 0; k < 2; ++k) dst[m][k] = *(const LAS bf16x8*)(lds + PG8_SA(b, h) + aoff + m * 2048 + k * 1024); } while (0)
; #define PG8_LDB(dst, b, h) do { _Pragma("unroll") for (int n = 0; n < 2; ++n) _Pragma("unroll") for (int k = 0; k < 2; ++k) dst[n][k] = *(const LAS bf16x8*)(lds + PG8_SB(b, h) + boff + n * 2048 + k * 1024); } while (0)
; #define PG8_MMA(ai, bj, At, Bt) do { __builtin_amdgcn_s_setprio(1); _Pragma("unroll") for (int m = 0; m < 4; ++m) _Pragma("unroll") for (int n = 0; n < 2; ++n) _Pragma("unroll") for (int k = 0; k < 2; ++k) \
;         acc[ai][bj][m][n] = __builtin_amdgcn_mfma_f32_16x16x32_bf16(Bt[n][k], At[m][k], acc[ai][bj][m][n], 0, 0, 0); __builtin_amdgcn_s_setprio(0); } while (0)
; #define PG8_WAIT_V(n) asm volatile("s_waitcnt vmcnt(" #n ")" ::: "memory")
; #define PG8_WAIT_L(n) asm volatile("s_waitcnt lgkmcnt(" #n ")" ::: "memory")
; template <class Epi, class Sched, bool ALIGN_EPI = false, bool SP2 = false>
; __device__ __forceinline__ void gemm_phase(LAS unsigned char* lds, const Gemm g, const Sched& S, const Epi& E) {
;     ...
;         for (int t = 0; t < nt; t += 2) {
;             const bool last = (t == nt - 2);
;             const char* a1 = cA + (size_t)(t + 1) * kstep;
;             const char* a2 = last ? nA : cA + (size_t)(t + 2) * kstep; const char* b2 = last ? nB : cB + (size_t)(t + 2) * kstep;
;             const char* a3 = a2 + kstep; const char* b3 = b2 + kstep;
;             if (last && has_next) S.a_ready(nxt);
;             if constexpr (SP2) {
;             PG8_LDB(B0, 0, 0); PG8_LDB(B1, 0, 1); PG8_SCHED; PG8_LDA(At, 0, 0); PG8_STAGE(PG8_SA(1, 1), a1 + hstep, voffA);
;             PG8_WAIT_V(8); PG8_WAIT_L(0); PG8_BAR; PG8_MMA(0, 0, At, B0); PG8_MMA(0, 1, At, B1); PG8_BAR; PG8_SCHED;
;             PG8_LDA(At, 0, 1); PG8_STAGE(PG8_SB(0, 0), b2, voffB); PG8_STAGE(PG8_SB(0, 1), b2 + hstepB, voffB); PG8_STAGE(PG8_SA(0, 0), a2, voffA);
;             PG8_WAIT_V(8); PG8_WAIT_L(0); PG8_BAR; PG8_MMA(1, 0, At, B0); PG8_MMA(1, 1, At, B1); PG8_BAR; PG8_SCHED;
.LBB0_535:
	ds_read_b128 v[34:37], v203
	ds_read_b128 v[38:41], v203 offset:1024
	ds_read_b128 v[42:45], v203 offset:2048
	ds_read_b128 v[46:49], v203 offset:3072
	s_waitcnt vmcnt(0)
	ds_read_b128 v[98:101], v204
	ds_read_b128 v[102:105], v204 offset:1024
	ds_read_b128 v[106:109], v204 offset:2048
	ds_read_b128 v[110:113], v204 offset:3072
	s_add_u32 s21, s16, 0xfff80080
	s_addc_u32 s22, s17, -1
	s_cmp_eq_u32 s20, 28
	s_cselect_b32 s59, s0, s22
	s_cselect_b32 s58, s3, s21
	s_cselect_b32 s49, s14, s19
	s_cselect_b32 s48, s15, s18
	s_add_i32 m0, s30, 0xc000
	ds_read_b128 v[212:215], v205
	ds_read_b128 v[216:219], v205 offset:1024
	ds_read_b128 v[220:223], v205 offset:2048
	ds_read_b128 v[224:227], v205 offset:3072
	ds_read_b128 v[228:231], v205 offset:4096
	ds_read_b128 v[232:235], v205 offset:5120
	ds_read_b128 v[236:239], v205 offset:6144
	ds_read_b128 v[240:243], v205 offset:7168
	global_load_lds_dwordx4 v172, s[16:17]
	s_add_i32 m0, s30, 0xe000
	s_nop 0
	global_load_lds_dwordx4 v174, s[16:17]
	s_waitcnt vmcnt(8)
	s_waitcnt lgkmcnt(0)
	s_barrier
	s_waitcnt lgkmcnt(0)
	v_mfma_f32_16x16x32_bf16 v[158:161], v[34:37], v[212:215], v[158:161]
	v_mfma_f32_16x16x32_bf16 v[154:157], v[42:45], v[212:215], v[154:157]
	v_mfma_f32_16x16x32_bf16 v[142:145], v[34:37], v[220:223], v[142:145]
	v_mfma_f32_16x16x32_bf16 v[138:141], v[42:45], v[220:223], v[138:141]
	v_mfma_f32_16x16x32_bf16 v[126:129], v[34:37], v[228:231], v[126:129]
	v_mfma_f32_16x16x32_bf16 v[122:125], v[42:45], v[228:231], v[122:125]
	v_mfma_f32_16x16x32_bf16 v[94:97], v[34:37], v[236:239], v[94:97]
	v_mfma_f32_16x16x32_bf16 v[90:93], v[42:45], v[236:239], v[90:93]
	v_mfma_f32_16x16x32_bf16 v[158:161], v[38:41], v[216:219], v[158:161]
	v_mfma_f32_16x16x32_bf16 v[154:157], v[46:49], v[216:219], v[154:157]
	v_mfma_f32_16x16x32_bf16 v[142:145], v[38:41], v[224:227], v[142:145]
	v_mfma_f32_16x16x32_bf16 v[138:141], v[46:49], v[224:227], v[138:141]
	v_mfma_f32_16x16x32_bf16 v[126:129], v[38:41], v[232:235], v[126:129]
	v_mfma_f32_16x16x32_bf16 v[122:125], v[46:49], v[232:235], v[122:125]
	v_mfma_f32_16x16x32_bf16 v[94:97], v[38:41], v[240:243], v[94:97]
	v_mfma_f32_16x16x32_bf16 v[90:93], v[46:49], v[240:243], v[90:93]
	v_mfma_f32_16x16x32_bf16 v[150:153], v[98:101], v[212:215], v[150:153]
	v_mfma_f32_16x16x32_bf16 v[146:149], v[106:109], v[212:215], v[146:149]
	v_mfma_f32_16x16x32_bf16 v[134:137], v[98:101], v[220:223], v[134:137]
	v_mfma_f32_16x16x32_bf16 v[130:133], v[106:109], v[220:223], v[130:133]
	v_mfma_f32_16x16x32_bf16 v[118:121], v[98:101], v[228:231], v[118:121]
	v_mfma_f32_16x16x32_bf16 v[114:117], v[106:109], v[228:231], v[114:117]
	v_mfma_f32_16x16x32_bf16 v[86:89], v[98:101], v[236:239], v[86:89]
	v_mfma_f32_16x16x32_bf16 v[82:85], v[106:109], v[236:239], v[82:85]
	v_mfma_f32_16x16x32_bf16 v[150:153], v[102:105], v[216:219], v[150:153]
	v_mfma_f32_16x16x32_bf16 v[146:149], v[110:113], v[216:219], v[146:149]
	v_mfma_f32_16x16x32_bf16 v[134:137], v[102:105], v[224:227], v[134:137]
	v_mfma_f32_16x16x32_bf16 v[130:133], v[110:113], v[224:227], v[130:133]
	v_mfma_f32_16x16x32_bf16 v[118:121], v[102:105], v[232:235], v[118:121]
	v_mfma_f32_16x16x32_bf16 v[114:117], v[110:113], v[232:235], v[114:117]
	v_mfma_f32_16x16x32_bf16 v[86:89], v[102:105], v[240:243], v[86:89]
	v_mfma_f32_16x16x32_bf16 v[82:85], v[110:113], v[240:243], v[82:85]
	s_barrier
	s_add_i32 s21, s68, s29
	s_mov_b32 m0, s21
	ds_read_b128 v[212:215], v205 offset:16384
	ds_read_b128 v[216:219], v205 offset:17408
	ds_read_b128 v[220:223], v205 offset:18432
	ds_read_b128 v[224:227], v205 offset:19456
	ds_read_b128 v[228:231], v205 offset:20480
	ds_read_b128 v[232:235], v205 offset:21504
	ds_read_b128 v[236:239], v205 offset:22528
	ds_read_b128 v[240:243], v205 offset:23552
	global_load_lds_dwordx4 v164, s[48:49]
	s_add_i32 m0, s21, 0x2000
	s_add_u32 s22, s48, 0x20000
	s_addc_u32 s23, s49, 0
	s_add_i32 s21, s69, s29
	global_load_lds_dwordx4 v168, s[48:49]
	s_mov_b32 m0, s21
	s_nop 0
	global_load_lds_dwordx4 v164, s[22:23]
	s_add_i32 m0, s21, 0x2000
	s_nop 0
	global_load_lds_dwordx4 v168, s[22:23]
	s_mov_b32 m0, s30
	s_nop 0
	global_load_lds_dwordx4 v162, s[58:59]
	s_mov_b32 m0, s31
	s_nop 0
	global_load_lds_dwordx4 v166, s[58:59]
	s_waitcnt vmcnt(8)
	s_waitcnt lgkmcnt(0)
	s_barrier
	s_waitcnt lgkmcnt(0)
	v_mfma_f32_16x16x32_bf16 v[78:81], v[34:37], v[212:215], v[78:81]
	v_mfma_f32_16x16x32_bf16 v[74:77], v[42:45], v[212:215], v[74:77]
	v_mfma_f32_16x16x32_bf16 v[62:65], v[34:37], v[220:223], v[62:65]
	v_mfma_f32_16x16x32_bf16 v[58:61], v[42:45], v[220:223], v[58:61]
	v_mfma_f32_16x16x32_bf16 v[30:33], v[34:37], v[228:231], v[30:33]
	v_mfma_f32_16x16x32_bf16 v[26:29], v[42:45], v[228:231], v[26:29]
	v_mfma_f32_16x16x32_bf16 v[14:17], v[34:37], v[236:239], v[14:17]
	v_mfma_f32_16x16x32_bf16 v[10:13], v[42:45], v[236:239], v[10:13]
	v_mfma_f32_16x16x32_bf16 v[78:81], v[38:41], v[216:219], v[78:81]
	v_mfma_f32_16x16x32_bf16 v[74:77], v[46:49], v[216:219], v[74:77]
	v_mfma_f32_16x16x32_bf16 v[62:65], v[38:41], v[224:227], v[62:65]
	v_mfma_f32_16x16x32_bf16 v[58:61], v[46:49], v[224:227], v[58:61]
	v_mfma_f32_16x16x32_bf16 v[30:33], v[38:41], v[232:235], v[30:33]
	v_mfma_f32_16x16x32_bf16 v[26:29], v[46:49], v[232:235], v[26:29]
	v_mfma_f32_16x16x32_bf16 v[14:17], v[38:41], v[240:243], v[14:17]
	v_mfma_f32_16x16x32_bf16 v[10:13], v[46:49], v[240:243], v[10:13]
	v_mfma_f32_16x16x32_bf16 v[22:25], v[98:101], v[228:231], v[22:25]
	v_mfma_f32_16x16x32_bf16 v[18:21], v[106:109], v[228:231], v[18:21]
	v_mfma_f32_16x16x32_bf16 v[6:9], v[98:101], v[236:239], v[6:9]
	v_mfma_f32_16x16x32_bf16 v[2:5], v[106:109], v[236:239], v[2:5]
	v_mfma_f32_16x16x32_bf16 v[34:37], v[98:101], v[212:215], v[70:73]
	v_mfma_f32_16x16x32_bf16 v[38:41], v[106:109], v[212:215], v[66:69]
	v_mfma_f32_16x16x32_bf16 v[42:45], v[98:101], v[220:223], v[54:57]
	v_mfma_f32_16x16x32_bf16 v[46:49], v[106:109], v[220:223], v[50:53]
	v_mfma_f32_16x16x32_bf16 v[22:25], v[102:105], v[232:235], v[22:25]
	v_mfma_f32_16x16x32_bf16 v[18:21], v[110:113], v[232:235], v[18:21]
	v_mfma_f32_16x16x32_bf16 v[6:9], v[102:105], v[240:243], v[6:9]
	v_mfma_f32_16x16x32_bf16 v[2:5], v[110:113], v[240:243], v[2:5]
	v_mfma_f32_16x16x32_bf16 v[34:37], v[102:105], v[216:219], v[34:37]
	v_mfma_f32_16x16x32_bf16 v[38:41], v[110:113], v[216:219], v[38:41]
	v_mfma_f32_16x16x32_bf16 v[42:45], v[102:105], v[224:227], v[42:45]
	v_mfma_f32_16x16x32_bf16 v[46:49], v[110:113], v[224:227], v[46:49]
	s_barrier
; #define PG8_STAGE(bufoff, gbase, voff) do { _Pragma("unroll") for (int _i = 0; _i < 2; ++_i) \
;         __builtin_amdgcn_global_load_lds((const unsigned*)((const char*)(gbase) + (voff)[_i]), (LAS unsigned*)(lds + (bufoff) + ldsw + _i * 8192), 16, 0, 0); } while (0)
; #define PG8_LDA(dst, b, h) do { _Pragma("unroll") for (int m = 0; m < 4; ++m) _Pragma("unroll") for (int k = 0; k < 2; ++k) dst[m][k] = *(const LAS bf16x8*)(lds + PG8_SA(b, h) + aoff + m * 2048 + k * 1024); } while (0)
; #define PG8_LDB(dst, b, h) do { _Pragma("unroll") for (int n = 0; n < 2; ++n) _Pragma("unroll") for (int k = 0; k < 2; ++k) dst[n][k] = *(const LAS bf16x8*)(lds + PG8_SB(b, h) + boff + n * 2048 + k * 1024); } while (0)
; #define PG8_MMA(ai, bj, At, Bt) do { __builtin_amdgcn_s_setprio(1); _Pragma("unroll") for (int m = 0; m < 4; ++m) _Pragma("unroll") for (int n = 0; n < 2; ++n) _Pragma("unroll") for (int k = 0; k < 2; ++k) \
;         acc[ai][bj][m][n] = __builtin_amdgcn_mfma_f32_16x16x32_bf16(Bt[n][k], At[m][k], acc[ai][bj][m][n], 0, 0, 0); __builtin_amdgcn_s_setprio(0); } while (0)
; #define PG8_WAIT_V(n) asm volatile("s_waitcnt vmcnt(" #n ")" ::: "memory")
; #define PG8_WAIT_L(n) asm volatile("s_waitcnt lgkmcnt(" #n ")" ::: "memory")
; #define PG8_BAR __builtin_amdgcn_s_barrier()
; #define PG8_SCHED __builtin_amdgcn_sched_barrier(0)
; template <class Epi, class Sched, bool ALIGN_EPI = false, bool SP2 = false>
; __device__ __forceinline__ void gemm_phase(LAS unsigned char* lds, const Gemm g, const Sched& S, const Epi& E) {
;     ...
;             PG8_LDB(B0, 1, 0); PG8_LDB(B1, 1, 1); PG8_SCHED; PG8_LDA(At, 1, 0); PG8_STAGE(PG8_SA(0, 1), a2 + hstep, voffA);
;             PG8_WAIT_V(8); PG8_WAIT_L(0); PG8_BAR; PG8_MMA(0, 0, At, B0); PG8_MMA(0, 1, At, B1); PG8_BAR; PG8_SCHED;
;             PG8_LDA(At, 1, 1); PG8_STAGE(PG8_SB(1, 0), b3, voffB); PG8_STAGE(PG8_SB(1, 1), b3 + hstepB, voffB); PG8_STAGE(PG8_SA(1, 0), a3, voffA);
;             PG8_WAIT_V(8); PG8_WAIT_L(0); PG8_BAR; PG8_MMA(1, 0, At, B0); PG8_MMA(1, 1, At, B1); PG8_BAR; PG8_SCHED;
	s_add_i32 s21, 0, 0x18000
	s_add_i32 s24, 0, 0x1c000
	v_add_u32_e32 v70, s21, v186
	v_add_u32_e32 v110, s24, v186
	ds_read_b128 v[50:53], v70
	ds_read_b128 v[54:57], v70 offset:1024
	ds_read_b128 v[66:69], v70 offset:2048
	ds_read_b128 v[70:73], v70 offset:3072
	ds_read_b128 v[98:101], v110
	ds_read_b128 v[102:105], v110 offset:1024
	ds_read_b128 v[106:109], v110 offset:2048
	ds_read_b128 v[110:113], v110 offset:3072
	s_add_u32 s22, s58, 0x80000
	s_addc_u32 s23, s59, 0
	s_mov_b32 m0, s33
	ds_read_b128 v[212:215], v205 offset:32768
	ds_read_b128 v[216:219], v205 offset:33792
	ds_read_b128 v[220:223], v205 offset:34816
	ds_read_b128 v[224:227], v205 offset:35840
	ds_read_b128 v[228:231], v205 offset:36864
	ds_read_b128 v[232:235], v205 offset:37888
	ds_read_b128 v[236:239], v205 offset:38912
	ds_read_b128 v[240:243], v205 offset:39936
	global_load_lds_dwordx4 v162, s[22:23]
	s_mov_b32 m0, s60
	s_nop 0
	global_load_lds_dwordx4 v166, s[22:23]
	s_waitcnt vmcnt(8)
	s_waitcnt lgkmcnt(0)
	s_barrier
	s_waitcnt lgkmcnt(0)
	v_mfma_f32_16x16x32_bf16 v[158:161], v[50:53], v[212:215], v[158:161]
	v_mfma_f32_16x16x32_bf16 v[154:157], v[66:69], v[212:215], v[154:157]
	v_mfma_f32_16x16x32_bf16 v[142:145], v[50:53], v[220:223], v[142:145]
	v_mfma_f32_16x16x32_bf16 v[138:141], v[66:69], v[220:223], v[138:141]
	v_mfma_f32_16x16x32_bf16 v[126:129], v[50:53], v[228:231], v[126:129]
	v_mfma_f32_16x16x32_bf16 v[122:125], v[66:69], v[228:231], v[122:125]
	v_mfma_f32_16x16x32_bf16 v[94:97], v[50:53], v[236:239], v[94:97]
	v_mfma_f32_16x16x32_bf16 v[90:93], v[66:69], v[236:239], v[90:93]
	v_mfma_f32_16x16x32_bf16 v[158:161], v[54:57], v[216:219], v[158:161]
	v_mfma_f32_16x16x32_bf16 v[154:157], v[70:73], v[216:219], v[154:157]
	v_mfma_f32_16x16x32_bf16 v[142:145], v[54:57], v[224:227], v[142:145]
	v_mfma_f32_16x16x32_bf16 v[138:141], v[70:73], v[224:227], v[138:141]
	v_mfma_f32_16x16x32_bf16 v[126:129], v[54:57], v[232:235], v[126:129]
	v_mfma_f32_16x16x32_bf16 v[122:125], v[70:73], v[232:235], v[122:125]
	v_mfma_f32_16x16x32_bf16 v[94:97], v[54:57], v[240:243], v[94:97]
	v_mfma_f32_16x16x32_bf16 v[90:93], v[70:73], v[240:243], v[90:93]
	v_mfma_f32_16x16x32_bf16 v[150:153], v[98:101], v[212:215], v[150:153]
	v_mfma_f32_16x16x32_bf16 v[146:149], v[106:109], v[212:215], v[146:149]
	v_mfma_f32_16x16x32_bf16 v[134:137], v[98:101], v[220:223], v[134:137]
	v_mfma_f32_16x16x32_bf16 v[130:133], v[106:109], v[220:223], v[130:133]
	v_mfma_f32_16x16x32_bf16 v[118:121], v[98:101], v[228:231], v[118:121]
	v_mfma_f32_16x16x32_bf16 v[114:117], v[106:109], v[228:231], v[114:117]
	v_mfma_f32_16x16x32_bf16 v[86:89], v[98:101], v[236:239], v[86:89]
	v_mfma_f32_16x16x32_bf16 v[82:85], v[106:109], v[236:239], v[82:85]
	v_mfma_f32_16x16x32_bf16 v[150:153], v[102:105], v[216:219], v[150:153]
	v_mfma_f32_16x16x32_bf16 v[146:149], v[110:113], v[216:219], v[146:149]
	v_mfma_f32_16x16x32_bf16 v[134:137], v[102:105], v[224:227], v[134:137]
	v_mfma_f32_16x16x32_bf16 v[130:133], v[110:113], v[224:227], v[130:133]
	v_mfma_f32_16x16x32_bf16 v[118:121], v[102:105], v[232:235], v[118:121]
	v_mfma_f32_16x16x32_bf16 v[114:117], v[110:113], v[232:235], v[114:117]
	v_mfma_f32_16x16x32_bf16 v[86:89], v[102:105], v[240:243], v[86:89]
	v_mfma_f32_16x16x32_bf16 v[82:85], v[110:113], v[240:243], v[82:85]
	s_barrier
	s_add_u32 s98, s48, 0x80
	s_addc_u32 s99, s49, 0
	s_add_u32 s100, s58, 0x80
	s_addc_u32 s101, s59, 0
	s_add_i32 s21, s21, s29
	s_mov_b32 m0, s21
	ds_read_b128 v[212:215], v205 offset:49152
	ds_read_b128 v[216:219], v205 offset:50176
	ds_read_b128 v[220:223], v205 offset:51200
	ds_read_b128 v[224:227], v205 offset:52224
	ds_read_b128 v[228:231], v205 offset:53248
	ds_read_b128 v[232:235], v205 offset:54272
	ds_read_b128 v[236:239], v205 offset:55296
	ds_read_b128 v[240:243], v205 offset:56320
	global_load_lds_dwordx4 v164, s[98:99]
	s_add_i32 m0, s21, 0x2000
	s_add_u32 s22, s48, 0x20080
	s_addc_u32 s23, s49, 0
	s_add_i32 s21, s24, s29
	global_load_lds_dwordx4 v168, s[98:99]
	s_mov_b32 m0, s21
	s_nop 0
	global_load_lds_dwordx4 v164, s[22:23]
	s_add_i32 m0, s21, 0x2000
	s_nop 0
	global_load_lds_dwordx4 v168, s[22:23]
	s_mov_b32 m0, s65
	s_nop 0
	global_load_lds_dwordx4 v162, s[100:101]
	s_mov_b32 m0, s66
	s_nop 0
	global_load_lds_dwordx4 v166, s[100:101]
	s_waitcnt vmcnt(8)
	s_waitcnt lgkmcnt(0)
	s_barrier
	s_waitcnt lgkmcnt(0)
	v_mfma_f32_16x16x32_bf16 v[78:81], v[50:53], v[212:215], v[78:81]
	v_mfma_f32_16x16x32_bf16 v[74:77], v[66:69], v[212:215], v[74:77]
	v_mfma_f32_16x16x32_bf16 v[62:65], v[50:53], v[220:223], v[62:65]
	v_mfma_f32_16x16x32_bf16 v[58:61], v[66:69], v[220:223], v[58:61]
	v_mfma_f32_16x16x32_bf16 v[30:33], v[50:53], v[228:231], v[30:33]
	v_mfma_f32_16x16x32_bf16 v[26:29], v[66:69], v[228:231], v[26:29]
	v_mfma_f32_16x16x32_bf16 v[14:17], v[50:53], v[236:239], v[14:17]
	v_mfma_f32_16x16x32_bf16 v[10:13], v[66:69], v[236:239], v[10:13]
	v_mfma_f32_16x16x32_bf16 v[78:81], v[54:57], v[216:219], v[78:81]
	v_mfma_f32_16x16x32_bf16 v[74:77], v[70:73], v[216:219], v[74:77]
	v_mfma_f32_16x16x32_bf16 v[62:65], v[54:57], v[224:227], v[62:65]
	v_mfma_f32_16x16x32_bf16 v[58:61], v[70:73], v[224:227], v[58:61]
	v_mfma_f32_16x16x32_bf16 v[30:33], v[54:57], v[232:235], v[30:33]
	v_mfma_f32_16x16x32_bf16 v[26:29], v[70:73], v[232:235], v[26:29]
	v_mfma_f32_16x16x32_bf16 v[14:17], v[54:57], v[240:243], v[14:17]
	v_mfma_f32_16x16x32_bf16 v[10:13], v[70:73], v[240:243], v[10:13]
	v_mfma_f32_16x16x32_bf16 v[34:37], v[98:101], v[212:215], v[34:37]
	v_mfma_f32_16x16x32_bf16 v[70:73], v[102:105], v[216:219], v[34:37]
	v_mfma_f32_16x16x32_bf16 v[34:37], v[106:109], v[212:215], v[38:41]
	v_mfma_f32_16x16x32_bf16 v[66:69], v[110:113], v[216:219], v[34:37]
	v_mfma_f32_16x16x32_bf16 v[34:37], v[98:101], v[220:223], v[42:45]
	v_mfma_f32_16x16x32_bf16 v[54:57], v[102:105], v[224:227], v[34:37]
	v_mfma_f32_16x16x32_bf16 v[34:37], v[106:109], v[220:223], v[46:49]
	v_mfma_f32_16x16x32_bf16 v[22:25], v[98:101], v[228:231], v[22:25]
	v_mfma_f32_16x16x32_bf16 v[18:21], v[106:109], v[228:231], v[18:21]
	v_mfma_f32_16x16x32_bf16 v[6:9], v[98:101], v[236:239], v[6:9]
	v_mfma_f32_16x16x32_bf16 v[2:5], v[106:109], v[236:239], v[2:5]
	v_mfma_f32_16x16x32_bf16 v[50:53], v[110:113], v[224:227], v[34:37]
	v_mfma_f32_16x16x32_bf16 v[22:25], v[102:105], v[232:235], v[22:25]
	v_mfma_f32_16x16x32_bf16 v[18:21], v[110:113], v[232:235], v[18:21]
	v_mfma_f32_16x16x32_bf16 v[6:9], v[102:105], v[240:243], v[6:9]
	v_mfma_f32_16x16x32_bf16 v[2:5], v[110:113], v[240:243], v[2:5]
	s_barrier
	s_add_i32 s20, s20, 2
	s_add_u32 s16, s16, 0x100
	s_addc_u32 s17, s17, 0
	s_add_u32 s18, s18, 0x100
	s_addc_u32 s19, s19, 0
	s_cmp_gt_u32 s20, 29
	s_cbranch_scc0 .LBB0_535
	s_setprio 0
; __device__ __forceinline__ float row_rstd(const float* ss, int row) { return 1.0f / sqrtf(ss[row] * (1.0f / DM) + 1e-6f); }
; #define PG8_BAR __builtin_amdgcn_s_barrier()
;     __device__ __forceinline__ void operator()(const f32x4 (&acc)[2][2][4][2], const Unit& u, int wr, int wc, int fr, int fq) const {
;         const int row0 = u.pm * BM + wr * 64 + fr, col0 = u.pn * BM + wc * 64 + 8 * fq;
;         const bool lat = u.pm < ML / BM; const int s = lat ? (u.pm >> 5) : 4;
;         const float* bp = bias + (size_t)s * BIAS_N + col0;
;         const f32x4 b00 = *(const f32x4*)bp, b01 = *(const f32x4*)(bp + 4), b10 = *(const f32x4*)(bp + 32), b11 = *(const f32x4*)(bp + 36);
;         const int lane = fq * 16 + fr;
;         const float rsl0 = row_rstd(ss, u.pm * BM + wr * 64 + lane), rsl1 = row_rstd(ss, u.pm * BM + HALF + wr * 64 + lane);
; template <class Epi, class Sched, bool ALIGN_EPI = false, bool SP2 = false>
; __device__ __forceinline__ void gemm_phase(LAS unsigned char* lds, const Gemm g, const Sched& S, const Epi& E) {
;     ...
;         if constexpr (ALIGN_EPI) { if (wr == 0) PG8_BAR; }
.LBB0_538:
	s_cmpk_lt_i32 s2, 0x80
	s_cselect_b64 s[48:49], -1, 0
	s_cmpk_gt_i32 s2, 0x7f
	s_mov_b64 s[16:17], 0xb000
	s_cbranch_scc1 .LBB0_540
	s_ashr_i32 s0, s2, 5
	s_mul_hi_i32 s17, s0, 0x2c00
	s_mul_i32 s16, s0, 0x2c00
.LBB0_540:
	s_lshl_b32 s0, s2, 8
	s_add_i32 s0, s0, s62
	s_lshl_b64 s[2:3], s[16:17], 2
	v_lshl_or_b32 v182, s46, 8, v202
	s_add_u32 s2, s63, s2
	v_or_b32_e32 v98, s0, v187
	s_addc_u32 s3, s64, s3
	v_ashrrev_i32_e32 v183, 31, v182
	v_ashrrev_i32_e32 v99, 31, v98
	v_lshl_add_u64 v[38:39], v[182:183], 2, s[2:3]
	v_lshl_add_u64 v[98:99], v[98:99], 2, s[74:75]
	global_load_dwordx4 v[42:45], v[38:39], off offset:16
	global_load_dwordx4 v[46:49], v[38:39], off
	global_load_dwordx4 v[34:37], v[38:39], off offset:144
	s_nop 0
	global_load_dwordx4 v[38:41], v[38:39], off offset:128
	s_cmp_lt_u32 s46, 13
	global_load_dword v98, v[98:99], off
	v_add_u32_e32 v110, s0, v193
	v_ashrrev_i32_e32 v111, 31, v110
	v_lshl_add_u64 v[110:111], v[110:111], 2, s[74:75]
	global_load_dword v112, v[110:111], off
	s_mov_b64 vcc, s[76:77]
	s_cbranch_vccz .Lalign_ip_14239
	s_barrier
.Lalign_ip_14239:
	s_waitcnt vmcnt(0)
	v_fmamk_f32 v98, v98, 0x3a000000, v206
	v_cmp_gt_f32_e32 vcc, s70, v98
	v_mul_f32_e32 v99, 0x4f800000, v98
	s_nop 0
	v_cndmask_b32_e32 v98, v98, v99, vcc
	v_sqrt_f32_e32 v99, v98
	s_nop 0
	v_add_u32_e32 v100, -1, v99
	v_fma_f32 v101, -v100, v99, v98
	v_cmp_ge_f32_e64 s[2:3], 0, v101
	v_add_u32_e32 v101, 1, v99
	s_nop 0
	v_cndmask_b32_e64 v100, v99, v100, s[2:3]
	v_fma_f32 v99, -v101, v99, v98
	v_cmp_lt_f32_e64 s[2:3], 0, v99
	s_nop 1
	v_cndmask_b32_e64 v99, v100, v101, s[2:3]
	v_mul_f32_e32 v100, 0x37800000, v99
	v_cndmask_b32_e32 v99, v99, v100, vcc
	v_cmp_class_f32_e32 vcc, v98, v207
	s_nop 1
	v_cndmask_b32_e32 v98, v99, v98, vcc
	v_div_scale_f32 v99, s[2:3], v98, v98, 1.0
	v_rcp_f32_e32 v100, v99
	s_nop 0
	v_fma_f32 v101, -v99, v100, 1.0
	v_fmac_f32_e32 v100, v101, v100
	v_div_scale_f32 v101, vcc, 1.0, v98, 1.0
	v_mul_f32_e32 v102, v101, v100
	v_fma_f32 v103, -v99, v102, v101
	v_fmac_f32_e32 v102, v103, v100
	v_fma_f32 v99, -v99, v102, v101
	v_div_fmas_f32 v99, v99, v100, v102
	v_div_fixup_f32 v216, v99, v98, 1.0
	v_fmamk_f32 v98, v112, 0x3a000000, v206
	v_cmp_gt_f32_e32 vcc, s70, v98
	v_mul_f32_e32 v99, 0x4f800000, v98
	s_nop 0
	v_cndmask_b32_e32 v98, v98, v99, vcc
	v_sqrt_f32_e32 v99, v98
	s_nop 0
	v_add_u32_e32 v100, -1, v99
	v_fma_f32 v101, -v100, v99, v98
	v_cmp_ge_f32_e64 s[2:3], 0, v101
	v_add_u32_e32 v101, 1, v99
	s_nop 0
	v_cndmask_b32_e64 v100, v99, v100, s[2:3]
	v_fma_f32 v99, -v101, v99, v98
	v_cmp_lt_f32_e64 s[2:3], 0, v99
	s_nop 1
	v_cndmask_b32_e64 v99, v100, v101, s[2:3]
	v_mul_f32_e32 v100, 0x37800000, v99
	v_cndmask_b32_e32 v99, v99, v100, vcc
	v_cmp_class_f32_e32 vcc, v98, v207
	s_nop 1
	v_cndmask_b32_e32 v98, v99, v98, vcc
	v_div_scale_f32 v99, s[2:3], v98, v98, 1.0
	v_rcp_f32_e32 v100, v99
	s_cselect_b64 s[2:3], -1, 0
	s_lshr_b32 s14, 0x100c, s46
	s_bitcmp1_b32 s14, 0
	v_fma_f32 v101, -v99, v100, 1.0
	v_fmac_f32_e32 v100, v101, v100
	v_div_scale_f32 v101, vcc, 1.0, v98, 1.0
	v_mul_f32_e32 v102, v101, v100
	v_fma_f32 v103, -v99, v102, v101
	v_fmac_f32_e32 v102, v103, v100
	s_cselect_b64 s[14:15], -1, 0
	v_fma_f32 v99, -v99, v102, v101
	s_and_b64 s[2:3], s[2:3], s[14:15]
	v_div_fmas_f32 v99, v99, v100, v102
	s_cmp_eq_u32 s46, 12
	v_and_or_b32 v100, v208, 64, v184
	v_and_b32_e32 v101, 64, v208
	s_cselect_b64 s[24:25], -1, 0
	s_mov_b64 s[46:47], -1
	s_and_b64 vcc, exec, s[2:3]
	v_add_u32_e32 v181, 64, v101
	v_lshlrev_b32_e32 v211, 2, v100
	s_cbranch_vccnz .LBB0_542
	v_add_u32_e32 v214, 64, v101
	v_lshlrev_b32_e32 v219, 2, v100
	s_mov_b64 s[46:47], 0

; #define PG8_STAGE(bufoff, gbase, voff) do { _Pragma("unroll") for (int _i = 0; _i < 2; ++_i) \
;         __builtin_amdgcn_global_load_lds((const unsigned*)((const char*)(gbase) + (voff)[_i]), (LAS unsigned*)(lds + (bufoff) + ldsw + _i * 8192), 16, 0, 0); } while (0)
; #define PG8_LDA(dst, b, h) do { _Pragma("unroll") for (int m = 0; m < 4; ++m) _Pragma("unroll") for (int k = 0; k < 2; ++k) dst[m][k] = *(const LAS bf16x8*)(lds + PG8_SA(b, h) + aoff + m * 2048 + k * 1024); } while (0)
; #define PG8_LDB(dst, b, h) do { _Pragma("unroll") for (int n = 0; n < 2; ++n) _Pragma("unroll") for (int k = 0; k < 2; ++k) dst[n][k] = *(const LAS bf16x8*)(lds + PG8_SB(b, h) + boff + n * 2048 + k * 1024); } while (0)
; #define PG8_MMA(ai, bj, At, Bt) do { __builtin_amdgcn_s_setprio(1); _Pragma("unroll") for (int m = 0; m < 4; ++m) _Pragma("unroll") for (int n = 0; n < 2; ++n) _Pragma("unroll") for (int k = 0; k < 2; ++k) \
;         acc[ai][bj][m][n] = __builtin_amdgcn_mfma_f32_16x16x32_bf16(Bt[n][k], At[m][k], acc[ai][bj][m][n], 0, 0, 0); __builtin_amdgcn_s_setprio(0); } while (0)
; #define PG8_WAIT_V(n) asm volatile("s_waitcnt vmcnt(" #n ")" ::: "memory")
; #define PG8_WAIT_L(n) asm volatile("s_waitcnt lgkmcnt(" #n ")" ::: "memory")
; template <class Epi, class Sched, bool ALIGN_EPI = false, bool SP2 = false>
; __device__ __forceinline__ void gemm_phase(LAS unsigned char* lds, const Gemm g, const Sched& S, const Epi& E) {
;     ...
;         for (int t = 0; t < nt; t += 2) {
;             const bool last = (t == nt - 2);
;             const char* a1 = cA + (size_t)(t + 1) * kstep;
;             const char* a2 = last ? nA : cA + (size_t)(t + 2) * kstep; const char* b2 = last ? nB : cB + (size_t)(t + 2) * kstep;
;             const char* a3 = a2 + kstep; const char* b3 = b2 + kstep;
;             if (last && has_next) S.a_ready(nxt);
;             if constexpr (SP2) {
;             PG8_LDB(B0, 0, 0); PG8_LDB(B1, 0, 1); PG8_SCHED; PG8_LDA(At, 0, 0); PG8_STAGE(PG8_SA(1, 1), a1 + hstep, voffA);
;             PG8_WAIT_V(8); PG8_WAIT_L(0); PG8_BAR; PG8_MMA(0, 0, At, B0); PG8_MMA(0, 1, At, B1); PG8_BAR; PG8_SCHED;
;             PG8_LDA(At, 0, 1); PG8_STAGE(PG8_SB(0, 0), b2, voffB); PG8_STAGE(PG8_SB(0, 1), b2 + hstepB, voffB); PG8_STAGE(PG8_SA(0, 0), a2, voffA);
;             PG8_WAIT_V(8); PG8_WAIT_L(0); PG8_BAR; PG8_MMA(1, 0, At, B0); PG8_MMA(1, 1, At, B1); PG8_BAR; PG8_SCHED;
.LBB0_2143:
	ds_read_b128 v[34:37], v202
	ds_read_b128 v[38:41], v202 offset:1024
	ds_read_b128 v[42:45], v202 offset:2048
	ds_read_b128 v[46:49], v202 offset:3072
	ds_read_b128 v[98:101], v203
	ds_read_b128 v[102:105], v203 offset:1024
	ds_read_b128 v[106:109], v203 offset:2048
	ds_read_b128 v[110:113], v203 offset:3072
	s_add_u32 s22, s20, 0xfff80080
	s_addc_u32 s23, s21, -1
	s_cmp_eq_u32 s34, 28
	s_cselect_b32 s37, s3, s23
	s_cselect_b32 s36, s13, s22
	s_cselect_b32 s23, s11, s25
	s_cselect_b32 s22, s19, s24
	s_add_i32 m0, s28, 0xc000
	ds_read_b128 v[210:213], v204
	ds_read_b128 v[214:217], v204 offset:1024
	ds_read_b128 v[218:221], v204 offset:2048
	ds_read_b128 v[222:225], v204 offset:3072
	ds_read_b128 v[226:229], v204 offset:4096
	ds_read_b128 v[230:233], v204 offset:5120
	ds_read_b128 v[234:237], v204 offset:6144
	ds_read_b128 v[238:241], v204 offset:7168
	global_load_lds_dwordx4 v174, s[20:21]
	s_add_i32 m0, s28, 0xe000
	s_nop 0
	global_load_lds_dwordx4 v172, s[20:21]
	s_waitcnt vmcnt(8)
	s_waitcnt lgkmcnt(0)
	s_barrier
	s_waitcnt lgkmcnt(0)
	v_mfma_f32_16x16x32_bf16 v[158:161], v[34:37], v[210:213], v[158:161]
	v_mfma_f32_16x16x32_bf16 v[154:157], v[42:45], v[210:213], v[154:157]
	v_mfma_f32_16x16x32_bf16 v[142:145], v[34:37], v[218:221], v[142:145]
	v_mfma_f32_16x16x32_bf16 v[138:141], v[42:45], v[218:221], v[138:141]
	v_mfma_f32_16x16x32_bf16 v[126:129], v[34:37], v[226:229], v[126:129]
	v_mfma_f32_16x16x32_bf16 v[122:125], v[42:45], v[226:229], v[122:125]
	v_mfma_f32_16x16x32_bf16 v[94:97], v[34:37], v[234:237], v[94:97]
	v_mfma_f32_16x16x32_bf16 v[90:93], v[42:45], v[234:237], v[90:93]
	v_mfma_f32_16x16x32_bf16 v[158:161], v[38:41], v[214:217], v[158:161]
	v_mfma_f32_16x16x32_bf16 v[154:157], v[46:49], v[214:217], v[154:157]
	v_mfma_f32_16x16x32_bf16 v[142:145], v[38:41], v[222:225], v[142:145]
	v_mfma_f32_16x16x32_bf16 v[138:141], v[46:49], v[222:225], v[138:141]
	v_mfma_f32_16x16x32_bf16 v[126:129], v[38:41], v[230:233], v[126:129]
	v_mfma_f32_16x16x32_bf16 v[122:125], v[46:49], v[230:233], v[122:125]
	v_mfma_f32_16x16x32_bf16 v[94:97], v[38:41], v[238:241], v[94:97]
	v_mfma_f32_16x16x32_bf16 v[90:93], v[46:49], v[238:241], v[90:93]
	v_mfma_f32_16x16x32_bf16 v[150:153], v[98:101], v[210:213], v[150:153]
	v_mfma_f32_16x16x32_bf16 v[146:149], v[106:109], v[210:213], v[146:149]
	v_mfma_f32_16x16x32_bf16 v[134:137], v[98:101], v[218:221], v[134:137]
	v_mfma_f32_16x16x32_bf16 v[130:133], v[106:109], v[218:221], v[130:133]
	v_mfma_f32_16x16x32_bf16 v[118:121], v[98:101], v[226:229], v[118:121]
	v_mfma_f32_16x16x32_bf16 v[114:117], v[106:109], v[226:229], v[114:117]
	v_mfma_f32_16x16x32_bf16 v[86:89], v[98:101], v[234:237], v[86:89]
	v_mfma_f32_16x16x32_bf16 v[82:85], v[106:109], v[234:237], v[82:85]
	v_mfma_f32_16x16x32_bf16 v[150:153], v[102:105], v[214:217], v[150:153]
	v_mfma_f32_16x16x32_bf16 v[146:149], v[110:113], v[214:217], v[146:149]
	v_mfma_f32_16x16x32_bf16 v[134:137], v[102:105], v[222:225], v[134:137]
	v_mfma_f32_16x16x32_bf16 v[130:133], v[110:113], v[222:225], v[130:133]
	v_mfma_f32_16x16x32_bf16 v[118:121], v[102:105], v[230:233], v[118:121]
	v_mfma_f32_16x16x32_bf16 v[114:117], v[110:113], v[230:233], v[114:117]
	v_mfma_f32_16x16x32_bf16 v[86:89], v[102:105], v[238:241], v[86:89]
	v_mfma_f32_16x16x32_bf16 v[82:85], v[110:113], v[238:241], v[82:85]
	s_barrier
	s_add_i32 s35, s56, s27
	s_mov_b32 m0, s35
	ds_read_b128 v[210:213], v204 offset:16384
	ds_read_b128 v[214:217], v204 offset:17408
	ds_read_b128 v[218:221], v204 offset:18432
	ds_read_b128 v[222:225], v204 offset:19456
	ds_read_b128 v[226:229], v204 offset:20480
	ds_read_b128 v[230:233], v204 offset:21504
	ds_read_b128 v[234:237], v204 offset:22528
	ds_read_b128 v[238:241], v204 offset:23552
	global_load_lds_dwordx4 v164, s[22:23]
	s_add_i32 m0, s35, 0x2000
	s_add_u32 s46, s22, 0x20000
	v_lshl_add_u64 v[242:243], s[22:23], 0, v[168:169]
	s_addc_u32 s47, s23, 0
	s_add_i32 s35, s57, s27
	global_load_lds_dwordx4 v168, s[22:23]
	s_mov_b32 m0, s35
	v_lshl_add_u64 v[246:247], s[36:37], 0, v[166:167]
	global_load_lds_dwordx4 v164, s[46:47]
	s_add_i32 m0, s35, 0x2000
	s_nop 0
	global_load_lds_dwordx4 v168, s[46:47]
	v_lshl_add_u64 v[244:245], s[36:37], 0, v[162:163]
	s_mov_b32 m0, s28
	s_nop 0
	global_load_lds_dwordx4 v162, s[36:37]
	s_mov_b32 m0, s29
	s_nop 0
	global_load_lds_dwordx4 v166, s[36:37]
	s_waitcnt vmcnt(8)
	s_waitcnt lgkmcnt(0)
	s_barrier
	s_waitcnt lgkmcnt(0)
	v_mfma_f32_16x16x32_bf16 v[78:81], v[34:37], v[210:213], v[78:81]
	v_mfma_f32_16x16x32_bf16 v[74:77], v[42:45], v[210:213], v[74:77]
	v_mfma_f32_16x16x32_bf16 v[62:65], v[34:37], v[218:221], v[62:65]
	v_mfma_f32_16x16x32_bf16 v[58:61], v[42:45], v[218:221], v[58:61]
	v_mfma_f32_16x16x32_bf16 v[30:33], v[34:37], v[226:229], v[30:33]
	v_mfma_f32_16x16x32_bf16 v[26:29], v[42:45], v[226:229], v[26:29]
	v_mfma_f32_16x16x32_bf16 v[14:17], v[34:37], v[234:237], v[14:17]
	v_mfma_f32_16x16x32_bf16 v[10:13], v[42:45], v[234:237], v[10:13]
	v_mfma_f32_16x16x32_bf16 v[78:81], v[38:41], v[214:217], v[78:81]
	v_mfma_f32_16x16x32_bf16 v[74:77], v[46:49], v[214:217], v[74:77]
	v_mfma_f32_16x16x32_bf16 v[62:65], v[38:41], v[222:225], v[62:65]
	v_mfma_f32_16x16x32_bf16 v[58:61], v[46:49], v[222:225], v[58:61]
	v_mfma_f32_16x16x32_bf16 v[30:33], v[38:41], v[230:233], v[30:33]
	v_mfma_f32_16x16x32_bf16 v[26:29], v[46:49], v[230:233], v[26:29]
	v_mfma_f32_16x16x32_bf16 v[14:17], v[38:41], v[238:241], v[14:17]
	v_mfma_f32_16x16x32_bf16 v[10:13], v[46:49], v[238:241], v[10:13]
	v_mfma_f32_16x16x32_bf16 v[22:25], v[98:101], v[226:229], v[22:25]
	v_mfma_f32_16x16x32_bf16 v[18:21], v[106:109], v[226:229], v[18:21]
	v_mfma_f32_16x16x32_bf16 v[6:9], v[98:101], v[234:237], v[6:9]
	v_mfma_f32_16x16x32_bf16 v[2:5], v[106:109], v[234:237], v[2:5]
	v_mfma_f32_16x16x32_bf16 v[34:37], v[98:101], v[210:213], v[70:73]
	v_mfma_f32_16x16x32_bf16 v[38:41], v[106:109], v[210:213], v[66:69]
	v_mfma_f32_16x16x32_bf16 v[42:45], v[98:101], v[218:221], v[54:57]
	v_mfma_f32_16x16x32_bf16 v[46:49], v[106:109], v[218:221], v[50:53]
	v_mfma_f32_16x16x32_bf16 v[22:25], v[102:105], v[230:233], v[22:25]
	v_mfma_f32_16x16x32_bf16 v[18:21], v[110:113], v[230:233], v[18:21]
	v_mfma_f32_16x16x32_bf16 v[6:9], v[102:105], v[238:241], v[6:9]
	v_mfma_f32_16x16x32_bf16 v[2:5], v[110:113], v[238:241], v[2:5]
	v_mfma_f32_16x16x32_bf16 v[34:37], v[102:105], v[214:217], v[34:37]
	v_mfma_f32_16x16x32_bf16 v[38:41], v[110:113], v[214:217], v[38:41]
	v_mfma_f32_16x16x32_bf16 v[42:45], v[102:105], v[222:225], v[42:45]
	v_mfma_f32_16x16x32_bf16 v[46:49], v[110:113], v[222:225], v[46:49]
	s_barrier
; #define PG8_STAGE(bufoff, gbase, voff) do { _Pragma("unroll") for (int _i = 0; _i < 2; ++_i) \
;         __builtin_amdgcn_global_load_lds((const unsigned*)((const char*)(gbase) + (voff)[_i]), (LAS unsigned*)(lds + (bufoff) + ldsw + _i * 8192), 16, 0, 0); } while (0)
; #define PG8_LDA(dst, b, h) do { _Pragma("unroll") for (int m = 0; m < 4; ++m) _Pragma("unroll") for (int k = 0; k < 2; ++k) dst[m][k] = *(const LAS bf16x8*)(lds + PG8_SA(b, h) + aoff + m * 2048 + k * 1024); } while (0)
; #define PG8_LDB(dst, b, h) do { _Pragma("unroll") for (int n = 0; n < 2; ++n) _Pragma("unroll") for (int k = 0; k < 2; ++k) dst[n][k] = *(const LAS bf16x8*)(lds + PG8_SB(b, h) + boff + n * 2048 + k * 1024); } while (0)
; #define PG8_MMA(ai, bj, At, Bt) do { __builtin_amdgcn_s_setprio(1); _Pragma("unroll") for (int m = 0; m < 4; ++m) _Pragma("unroll") for (int n = 0; n < 2; ++n) _Pragma("unroll") for (int k = 0; k < 2; ++k) \
;         acc[ai][bj][m][n] = __builtin_amdgcn_mfma_f32_16x16x32_bf16(Bt[n][k], At[m][k], acc[ai][bj][m][n], 0, 0, 0); __builtin_amdgcn_s_setprio(0); } while (0)
; #define PG8_WAIT_V(n) asm volatile("s_waitcnt vmcnt(" #n ")" ::: "memory")
; #define PG8_WAIT_L(n) asm volatile("s_waitcnt lgkmcnt(" #n ")" ::: "memory")
; #define PG8_BAR __builtin_amdgcn_s_barrier()
; #define PG8_SCHED __builtin_amdgcn_sched_barrier(0)
; template <class Epi, class Sched, bool ALIGN_EPI = false, bool SP2 = false>
; __device__ __forceinline__ void gemm_phase(LAS unsigned char* lds, const Gemm g, const Sched& S, const Epi& E) {
;     ...
;             PG8_LDB(B0, 1, 0); PG8_LDB(B1, 1, 1); PG8_SCHED; PG8_LDA(At, 1, 0); PG8_STAGE(PG8_SA(0, 1), a2 + hstep, voffA);
;             PG8_WAIT_V(8); PG8_WAIT_L(0); PG8_BAR; PG8_MMA(0, 0, At, B0); PG8_MMA(0, 1, At, B1); PG8_BAR; PG8_SCHED;
;             PG8_LDA(At, 1, 1); PG8_STAGE(PG8_SB(1, 0), b3, voffB); PG8_STAGE(PG8_SB(1, 1), b3 + hstepB, voffB); PG8_STAGE(PG8_SA(1, 0), a3, voffA);
;             PG8_WAIT_V(8); PG8_WAIT_L(0); PG8_BAR; PG8_MMA(1, 0, At, B0); PG8_MMA(1, 1, At, B1); PG8_BAR; PG8_SCHED;
	s_add_i32 s35, 0, 0x18000
	s_add_i32 s46, 0, 0x1c000
	v_add_u32_e32 v70, s35, v185
	v_add_u32_e32 v110, s46, v185
	ds_read_b128 v[50:53], v70
	ds_read_b128 v[54:57], v70 offset:1024
	ds_read_b128 v[66:69], v70 offset:2048
	ds_read_b128 v[70:73], v70 offset:3072
	ds_read_b128 v[98:101], v110
	ds_read_b128 v[102:105], v110 offset:1024
	ds_read_b128 v[106:109], v110 offset:2048
	ds_read_b128 v[110:113], v110 offset:3072
	s_add_u32 s36, s36, 0x80000
	s_addc_u32 s37, s37, 0
	s_mov_b32 m0, s30
	ds_read_b128 v[210:213], v204 offset:32768
	ds_read_b128 v[214:217], v204 offset:33792
	ds_read_b128 v[218:221], v204 offset:34816
	ds_read_b128 v[222:225], v204 offset:35840
	ds_read_b128 v[226:229], v204 offset:36864
	ds_read_b128 v[230:233], v204 offset:37888
	ds_read_b128 v[234:237], v204 offset:38912
	ds_read_b128 v[238:241], v204 offset:39936
	global_load_lds_dwordx4 v162, s[36:37]
	s_mov_b32 m0, s31
	s_nop 0
	global_load_lds_dwordx4 v166, s[36:37]
	s_waitcnt vmcnt(8)
	s_waitcnt lgkmcnt(0)
	s_barrier
	s_waitcnt lgkmcnt(0)
	v_mfma_f32_16x16x32_bf16 v[158:161], v[50:53], v[210:213], v[158:161]
	v_mfma_f32_16x16x32_bf16 v[154:157], v[66:69], v[210:213], v[154:157]
	v_mfma_f32_16x16x32_bf16 v[142:145], v[50:53], v[218:221], v[142:145]
	v_mfma_f32_16x16x32_bf16 v[138:141], v[66:69], v[218:221], v[138:141]
	v_mfma_f32_16x16x32_bf16 v[126:129], v[50:53], v[226:229], v[126:129]
	v_mfma_f32_16x16x32_bf16 v[122:125], v[66:69], v[226:229], v[122:125]
	v_mfma_f32_16x16x32_bf16 v[94:97], v[50:53], v[234:237], v[94:97]
	v_mfma_f32_16x16x32_bf16 v[90:93], v[66:69], v[234:237], v[90:93]
	v_mfma_f32_16x16x32_bf16 v[158:161], v[54:57], v[214:217], v[158:161]
	v_mfma_f32_16x16x32_bf16 v[154:157], v[70:73], v[214:217], v[154:157]
	v_mfma_f32_16x16x32_bf16 v[142:145], v[54:57], v[222:225], v[142:145]
	v_mfma_f32_16x16x32_bf16 v[138:141], v[70:73], v[222:225], v[138:141]
	v_mfma_f32_16x16x32_bf16 v[126:129], v[54:57], v[230:233], v[126:129]
	v_mfma_f32_16x16x32_bf16 v[122:125], v[70:73], v[230:233], v[122:125]
	v_mfma_f32_16x16x32_bf16 v[94:97], v[54:57], v[238:241], v[94:97]
	v_mfma_f32_16x16x32_bf16 v[90:93], v[70:73], v[238:241], v[90:93]
	v_mfma_f32_16x16x32_bf16 v[150:153], v[98:101], v[210:213], v[150:153]
	v_mfma_f32_16x16x32_bf16 v[146:149], v[106:109], v[210:213], v[146:149]
	v_mfma_f32_16x16x32_bf16 v[134:137], v[98:101], v[218:221], v[134:137]
	v_mfma_f32_16x16x32_bf16 v[130:133], v[106:109], v[218:221], v[130:133]
	v_mfma_f32_16x16x32_bf16 v[118:121], v[98:101], v[226:229], v[118:121]
	v_mfma_f32_16x16x32_bf16 v[114:117], v[106:109], v[226:229], v[114:117]
	v_mfma_f32_16x16x32_bf16 v[86:89], v[98:101], v[234:237], v[86:89]
	v_mfma_f32_16x16x32_bf16 v[82:85], v[106:109], v[234:237], v[82:85]
	v_mfma_f32_16x16x32_bf16 v[150:153], v[102:105], v[214:217], v[150:153]
	v_mfma_f32_16x16x32_bf16 v[146:149], v[110:113], v[214:217], v[146:149]
	v_mfma_f32_16x16x32_bf16 v[134:137], v[102:105], v[222:225], v[134:137]
	v_mfma_f32_16x16x32_bf16 v[130:133], v[110:113], v[222:225], v[130:133]
	v_mfma_f32_16x16x32_bf16 v[118:121], v[102:105], v[230:233], v[118:121]
	v_mfma_f32_16x16x32_bf16 v[114:117], v[110:113], v[230:233], v[114:117]
	v_mfma_f32_16x16x32_bf16 v[86:89], v[102:105], v[238:241], v[86:89]
	v_mfma_f32_16x16x32_bf16 v[82:85], v[110:113], v[238:241], v[82:85]
	s_barrier
	s_add_u32 s98, s22, 0x80
	s_addc_u32 s99, s23, 0
	s_add_i32 s35, s35, s27
	s_mov_b32 m0, s35
	ds_read_b128 v[210:213], v204 offset:49152
	ds_read_b128 v[214:217], v204 offset:50176
	ds_read_b128 v[218:221], v204 offset:51200
	ds_read_b128 v[222:225], v204 offset:52224
	ds_read_b128 v[226:229], v204 offset:53248
	ds_read_b128 v[230:233], v204 offset:54272
	ds_read_b128 v[234:237], v204 offset:55296
	ds_read_b128 v[238:241], v204 offset:56320
	global_load_lds_dwordx4 v164, s[98:99]
	s_add_i32 m0, s35, 0x2000
	s_add_u32 s22, s22, 0x20080
	v_lshl_add_u64 v[182:183], v[242:243], 0, s[4:5]
	s_addc_u32 s23, s23, 0
	s_add_i32 s35, s46, s27
	global_load_lds_dwordx4 v[182:183], off
	s_mov_b32 m0, s35
	s_nop 0
	global_load_lds_dwordx4 v164, s[22:23]
	s_add_i32 m0, s35, 0x2000
	s_nop 0
	global_load_lds_dwordx4 v168, s[22:23]
	v_lshl_add_u64 v[182:183], v[244:245], 0, s[4:5]
	s_mov_b32 m0, s53
	s_nop 0
	global_load_lds_dwordx4 v[182:183], off
	v_lshl_add_u64 v[182:183], v[246:247], 0, s[4:5]
	s_mov_b32 m0, s54
	s_nop 0
	global_load_lds_dwordx4 v[182:183], off
	s_waitcnt vmcnt(8)
	s_waitcnt lgkmcnt(0)
	s_barrier
	s_waitcnt lgkmcnt(0)
	v_mfma_f32_16x16x32_bf16 v[78:81], v[50:53], v[210:213], v[78:81]
	v_mfma_f32_16x16x32_bf16 v[74:77], v[66:69], v[210:213], v[74:77]
	v_mfma_f32_16x16x32_bf16 v[62:65], v[50:53], v[218:221], v[62:65]
	v_mfma_f32_16x16x32_bf16 v[58:61], v[66:69], v[218:221], v[58:61]
	v_mfma_f32_16x16x32_bf16 v[30:33], v[50:53], v[226:229], v[30:33]
	v_mfma_f32_16x16x32_bf16 v[26:29], v[66:69], v[226:229], v[26:29]
	v_mfma_f32_16x16x32_bf16 v[14:17], v[50:53], v[234:237], v[14:17]
	v_mfma_f32_16x16x32_bf16 v[10:13], v[66:69], v[234:237], v[10:13]
	v_mfma_f32_16x16x32_bf16 v[78:81], v[54:57], v[214:217], v[78:81]
	v_mfma_f32_16x16x32_bf16 v[74:77], v[70:73], v[214:217], v[74:77]
	v_mfma_f32_16x16x32_bf16 v[62:65], v[54:57], v[222:225], v[62:65]
	v_mfma_f32_16x16x32_bf16 v[58:61], v[70:73], v[222:225], v[58:61]
	v_mfma_f32_16x16x32_bf16 v[30:33], v[54:57], v[230:233], v[30:33]
	v_mfma_f32_16x16x32_bf16 v[26:29], v[70:73], v[230:233], v[26:29]
	v_mfma_f32_16x16x32_bf16 v[14:17], v[54:57], v[238:241], v[14:17]
	v_mfma_f32_16x16x32_bf16 v[10:13], v[70:73], v[238:241], v[10:13]
	v_mfma_f32_16x16x32_bf16 v[34:37], v[98:101], v[210:213], v[34:37]
	v_mfma_f32_16x16x32_bf16 v[70:73], v[102:105], v[214:217], v[34:37]
	v_mfma_f32_16x16x32_bf16 v[34:37], v[106:109], v[210:213], v[38:41]
	v_mfma_f32_16x16x32_bf16 v[66:69], v[110:113], v[214:217], v[34:37]
	v_mfma_f32_16x16x32_bf16 v[34:37], v[98:101], v[218:221], v[42:45]
	v_mfma_f32_16x16x32_bf16 v[54:57], v[102:105], v[222:225], v[34:37]
	v_mfma_f32_16x16x32_bf16 v[34:37], v[106:109], v[218:221], v[46:49]
	v_mfma_f32_16x16x32_bf16 v[22:25], v[98:101], v[226:229], v[22:25]
	v_mfma_f32_16x16x32_bf16 v[18:21], v[106:109], v[226:229], v[18:21]
	v_mfma_f32_16x16x32_bf16 v[6:9], v[98:101], v[234:237], v[6:9]
	v_mfma_f32_16x16x32_bf16 v[2:5], v[106:109], v[234:237], v[2:5]
	v_mfma_f32_16x16x32_bf16 v[50:53], v[110:113], v[222:225], v[34:37]
	v_mfma_f32_16x16x32_bf16 v[22:25], v[102:105], v[230:233], v[22:25]
	v_mfma_f32_16x16x32_bf16 v[18:21], v[110:113], v[230:233], v[18:21]
	v_mfma_f32_16x16x32_bf16 v[6:9], v[102:105], v[238:241], v[6:9]
	v_mfma_f32_16x16x32_bf16 v[2:5], v[110:113], v[238:241], v[2:5]
	s_barrier
	s_add_i32 s34, s34, 2
	s_add_u32 s24, s24, 0x100
	s_addc_u32 s25, s25, 0
	s_add_u32 s20, s20, 0x100
	s_addc_u32 s21, s21, 0
	s_cmp_lt_u32 s34, 30
	s_cbranch_scc1 .LBB0_2143
	s_setprio 0
; __device__ __forceinline__ float row_rstd(const float* ss, int row) { return 1.0f / sqrtf(ss[row] * (1.0f / DM) + 1e-6f); }
; #define PG8_BAR __builtin_amdgcn_s_barrier()
;     __device__ __forceinline__ void operator()(const f32x4 (&acc)[2][2][4][2], const Unit& u, int wr, int wc, int fr, int fq) const {
;         const int row0 = u.pm * BM + wr * 64 + fr, col0 = u.pn * BM + wc * 64 + 8 * fq;
;         const bool lat = u.pm < ML / BM; const int s = lat ? (u.pm >> 5) : 4;
;         const float* bp = bias + (size_t)s * BIAS_N + col0;
;         const f32x4 b00 = *(const f32x4*)bp, b01 = *(const f32x4*)(bp + 4), b10 = *(const f32x4*)(bp + 32), b11 = *(const f32x4*)(bp + 36);
;         const int lane = fq * 16 + fr;
;         const float rsl0 = row_rstd(ss, u.pm * BM + wr * 64 + lane), rsl1 = row_rstd(ss, u.pm * BM + HALF + wr * 64 + lane);
; template <class Epi, class Sched, bool ALIGN_EPI = false, bool SP2 = false>
; __device__ __forceinline__ void gemm_phase(LAS unsigned char* lds, const Gemm g, const Sched& S, const Epi& E) {
;     ...
;         if constexpr (ALIGN_EPI) { if (wr == 0) PG8_BAR; }
.LBB0_2146:
	s_cmpk_lt_i32 s2, 0x80
	v_readlane_b32 s34, v252, 37
	s_cselect_b64 s[20:21], -1, 0
	s_cmpk_gt_i32 s2, 0x7f
	s_mov_b64 s[22:23], 0xb000
	v_readlane_b32 s35, v252, 38
	s_cbranch_scc1 .LBB0_2148
	s_ashr_i32 s3, s2, 5
	s_mul_hi_i32 s23, s3, 0x2c00
	s_mul_i32 s22, s3, 0x2c00
.LBB0_2148:
	s_lshl_b32 s11, s2, 8
	s_add_i32 s11, s11, s50
	s_lshl_b64 s[2:3], s[22:23], 2
	v_lshl_or_b32 v182, s18, 8, v201
	s_add_u32 s2, s51, s2
	v_or_b32_e32 v98, s11, v186
	s_addc_u32 s3, s52, s3
	v_ashrrev_i32_e32 v183, 31, v182
	v_ashrrev_i32_e32 v99, 31, v98
	v_lshl_add_u64 v[38:39], v[182:183], 2, s[2:3]
	v_lshl_add_u64 v[98:99], v[98:99], 2, s[6:7]
	global_load_dwordx4 v[42:45], v[38:39], off offset:16
	global_load_dwordx4 v[46:49], v[38:39], off
	global_load_dwordx4 v[34:37], v[38:39], off offset:144
	s_nop 0
	global_load_dwordx4 v[38:41], v[38:39], off offset:128
	s_cmp_lt_u32 s18, 13
	global_load_dword v98, v[98:99], off
	v_add_u32_e32 v110, s11, v192
	v_ashrrev_i32_e32 v111, 31, v110
	v_lshl_add_u64 v[110:111], v[110:111], 2, s[6:7]
	global_load_dword v112, v[110:111], off
	s_mov_b64 vcc, s[8:9]
	s_cbranch_vccz .Lalign_ip_57021
	s_barrier
.Lalign_ip_57021:
	s_waitcnt vmcnt(0)
	v_fmamk_f32 v98, v98, 0x3a000000, v205
	v_cmp_gt_f32_e32 vcc, s58, v98
	v_mul_f32_e32 v99, 0x4f800000, v98
	s_nop 0
	v_cndmask_b32_e32 v98, v98, v99, vcc
	v_sqrt_f32_e32 v99, v98
	s_nop 0
	v_add_u32_e32 v100, -1, v99
	v_fma_f32 v101, -v100, v99, v98
	v_cmp_ge_f32_e64 s[2:3], 0, v101
	v_add_u32_e32 v101, 1, v99
	s_nop 0
	v_cndmask_b32_e64 v100, v99, v100, s[2:3]
	v_fma_f32 v99, -v101, v99, v98
	v_cmp_lt_f32_e64 s[2:3], 0, v99
	s_nop 1
	v_cndmask_b32_e64 v99, v100, v101, s[2:3]
	v_mul_f32_e32 v100, 0x37800000, v99
	v_cndmask_b32_e32 v99, v99, v100, vcc
	v_cmp_class_f32_e32 vcc, v98, v206
	s_nop 1
	v_cndmask_b32_e32 v98, v99, v98, vcc
	v_div_scale_f32 v99, s[2:3], v98, v98, 1.0
	v_rcp_f32_e32 v100, v99
	s_nop 0
	v_fma_f32 v101, -v99, v100, 1.0
	v_fmac_f32_e32 v100, v101, v100
	v_div_scale_f32 v101, vcc, 1.0, v98, 1.0
	v_mul_f32_e32 v102, v101, v100
	v_fma_f32 v103, -v99, v102, v101
	v_fmac_f32_e32 v102, v103, v100
	v_fma_f32 v99, -v99, v102, v101
	v_div_fmas_f32 v99, v99, v100, v102
	v_div_fixup_f32 v215, v99, v98, 1.0
	v_fmamk_f32 v98, v112, 0x3a000000, v205
	v_cmp_gt_f32_e32 vcc, s58, v98
	v_mul_f32_e32 v99, 0x4f800000, v98
	s_nop 0
	v_cndmask_b32_e32 v98, v98, v99, vcc
	v_sqrt_f32_e32 v99, v98
	s_nop 0
	v_add_u32_e32 v100, -1, v99
	v_fma_f32 v101, -v100, v99, v98
	v_cmp_ge_f32_e64 s[2:3], 0, v101
	v_add_u32_e32 v101, 1, v99
	s_nop 0
	v_cndmask_b32_e64 v100, v99, v100, s[2:3]
	v_fma_f32 v99, -v101, v99, v98
	v_cmp_lt_f32_e64 s[2:3], 0, v99
	s_nop 1
	v_cndmask_b32_e64 v99, v100, v101, s[2:3]
	v_mul_f32_e32 v100, 0x37800000, v99
	v_cndmask_b32_e32 v99, v99, v100, vcc
	v_cmp_class_f32_e32 vcc, v98, v206
	s_nop 1
	v_cndmask_b32_e32 v98, v99, v98, vcc
	v_div_scale_f32 v99, s[2:3], v98, v98, 1.0
	v_rcp_f32_e32 v100, v99
	s_cselect_b64 s[2:3], -1, 0
	s_lshr_b32 s13, 0x100c, s18
	s_bitcmp1_b32 s13, 0
	v_fma_f32 v101, -v99, v100, 1.0
	v_fmac_f32_e32 v100, v101, v100
	v_div_scale_f32 v101, vcc, 1.0, v98, 1.0
	v_mul_f32_e32 v102, v101, v100
	v_fma_f32 v103, -v99, v102, v101
	v_fmac_f32_e32 v102, v103, v100
	s_cselect_b64 s[22:23], -1, 0
	v_fma_f32 v99, -v99, v102, v101
	s_and_b64 s[2:3], s[2:3], s[22:23]
	v_div_fmas_f32 v99, v99, v100, v102
	s_cmp_eq_u32 s18, 12
	v_and_or_b32 v100, v207, 64, v1
	v_and_b32_e32 v101, 64, v207
	s_cselect_b64 s[18:19], -1, 0
	s_mov_b64 s[22:23], -1
	s_and_b64 vcc, exec, s[2:3]
	v_add_u32_e32 v181, 64, v101
	v_lshlrev_b32_e32 v210, 2, v100
	s_cbranch_vccnz .LBB0_2150
	v_add_u32_e32 v213, 64, v101
	v_lshlrev_b32_e32 v218, 2, v100
	s_mov_b64 s[22:23], 0
